# v15 plus: w_in GEMM epilogue takes a straight-line cvt+store path for the MQK and MV column tiles instead of re-testing the column-tile ranges in each of 32 sub-blocks
# speedup vs baseline: 1.0270x; 1.0038x over previous
;     __device__ __forceinline__ void st4(bf16_t* p, f32x4 v) const { u32x2 w; w.x = cvt_pk_bf16(v[0], v[1]); w.y = cvt_pk_bf16(v[2], v[3]); *(u32x2*)p = w; }
;     __device__ __forceinline__ void operator()(const f32x4 (&acc)[2][2][4][2], const pg8::Unit& u, int wr, int wc, int fr, int fq) const {
;     ...
;             const int cc0 = wc * 32 + 4 * fq;
; #pragma unroll
;             for (int ai = 0; ai < 2; ++ai)
; #pragma unroll
;                 for (int m = 0; m < 4; ++m) {
;                     const int gr = grow0 + ai * 128 + m * 16;
;                     int bidx, tok; if (isctx) { bidx = (gr - NLAT) >> 8; tok = (gr - NLAT) & 255; } else { bidx = gr >> 11; tok = gr & 2047; }
; #pragma unroll
;                     for (int bj = 0; bj < 2; ++bj)
; #pragma unroll
;                         for (int n = 0; n < 2; ++n) {
;                             const int cc = cc0 + bj * 128 + n * 16; const f32x4 v = acc[ai][bj][m][n];
;                             if (pn == 5) st4(V + ((size_t)bidx * SKV + (isctx ? tok : TCX + tok)) * 256 + cc, v);
;                             else if (pn < 14) st4(MQK + (size_t)gr * 2048 + (pn - 6) * 256 + cc, v);
;                             else if (pn < 18) st4(MV + (size_t)gr * 1024 + (pn - 14) * 256 + cc, v);
.LBB0_248:
	s_cmp_lg_u32 s43, 5
	s_cselect_b64 s[20:21], -1, 0
	s_cmp_gt_u32 s43, 13
	s_cselect_b64 s[22:23], -1, 0
	s_cmp_gt_u32 s43, 17
	s_cselect_b64 s[70:71], -1, 0
	s_cmp_gt_u32 s43, 21
	v_readlane_b32 s3, v255, 15
	s_cselect_b64 s[68:69], -1, 0
	s_lshl_b32 s39, s43, 8
	v_ashrrev_i32_e32 v155, 31, v154
	v_lshl_add_u32 v134, v167, 2, s3
	v_cmp_lt_i32_e64 s[36:37], 1, v167
	s_add_i32 s66, s39, 0xfffffa00
	s_mov_b32 s67, s64
	v_lshlrev_b64 v[156:157], 7, v[154:155]
	v_lshlrev_b64 v[144:145], 11, v[154:155]
	v_lshlrev_b64 v[142:143], 12, v[154:155]
	s_cmp_lt_u32 s43, 6
	s_cbranch_scc1 .Lwin_gen
	s_cmp_gt_u32 s43, 17
	s_cbranch_scc1 .Lwin_gen
	s_cmp_gt_u32 s43, 13
	s_cbranch_scc1 .Lwin_mv
	v_readlane_b32 s16, v255, 27
	v_readlane_b32 s17, v255, 28
	v_ashrrev_i32_e32 v135, 31, v134
	s_nop 1
	v_lshl_add_u64 v[130:131], s[16:17], 0, v[142:143]
	v_lshl_add_u64 v[130:131], s[66:67], 1, v[130:131]
	v_lshl_add_u64 v[130:131], v[134:135], 1, v[130:131]
	s_mov_b64 s[28:29], 0x10000
	s_mov_b64 s[30:31], 0x50000
	s_branch .Lwin_st
.Lwin_mv:
	v_readlane_b32 s16, v255, 29
	v_readlane_b32 s17, v255, 30
	v_ashrrev_i32_e32 v135, 31, v134
	s_add_i32 s28, s39, 0xfffff200
	s_mov_b32 s29, 0
	v_lshl_add_u64 v[130:131], s[16:17], 0, v[144:145]
	v_lshl_add_u64 v[130:131], s[28:29], 1, v[130:131]
	v_lshl_add_u64 v[130:131], v[134:135], 1, v[130:131]
	s_mov_b64 s[28:29], 0x8000
	s_mov_b64 s[30:31], 0x28000
.Lwin_st:
	v_cvt_pk_bf16_f32 v132, v126, v127
	v_cvt_pk_bf16_f32 v133, v128, v129
	v_cvt_pk_bf16_f32 v134, v122, v123
	v_cvt_pk_bf16_f32 v135, v124, v125
	v_cvt_pk_bf16_f32 v136, v118, v119
	v_cvt_pk_bf16_f32 v137, v120, v121
	v_cvt_pk_bf16_f32 v138, v114, v115
	v_cvt_pk_bf16_f32 v139, v116, v117
	global_store_dwordx2 v[130:131], v[132:133], off
	global_store_dwordx2 v[130:131], v[134:135], off offset:32
	global_store_dwordx2 v[130:131], v[136:137], off offset:256
	global_store_dwordx2 v[130:131], v[138:139], off offset:288
	v_lshl_add_u64 v[130:131], v[130:131], 0, s[28:29]
	v_cvt_pk_bf16_f32 v132, v110, v111
	v_cvt_pk_bf16_f32 v133, v112, v113
	v_cvt_pk_bf16_f32 v134, v106, v107
	v_cvt_pk_bf16_f32 v135, v108, v109
	v_cvt_pk_bf16_f32 v136, v102, v103
	v_cvt_pk_bf16_f32 v137, v104, v105
	v_cvt_pk_bf16_f32 v138, v98, v99
	v_cvt_pk_bf16_f32 v139, v100, v101
	global_store_dwordx2 v[130:131], v[132:133], off
	global_store_dwordx2 v[130:131], v[134:135], off offset:32
	global_store_dwordx2 v[130:131], v[136:137], off offset:256
	global_store_dwordx2 v[130:131], v[138:139], off offset:288
	v_lshl_add_u64 v[130:131], v[130:131], 0, s[28:29]
	v_cvt_pk_bf16_f32 v132, v92, v93
	v_cvt_pk_bf16_f32 v133, v94, v95
	v_cvt_pk_bf16_f32 v134, v88, v89
	v_cvt_pk_bf16_f32 v135, v90, v91
	v_cvt_pk_bf16_f32 v136, v84, v85
	v_cvt_pk_bf16_f32 v137, v86, v87
	v_cvt_pk_bf16_f32 v138, v80, v81
	v_cvt_pk_bf16_f32 v139, v82, v83
	global_store_dwordx2 v[130:131], v[132:133], off
	global_store_dwordx2 v[130:131], v[134:135], off offset:32
	global_store_dwordx2 v[130:131], v[136:137], off offset:256
	global_store_dwordx2 v[130:131], v[138:139], off offset:288
	v_lshl_add_u64 v[130:131], v[130:131], 0, s[28:29]
	v_cvt_pk_bf16_f32 v132, v76, v77
	v_cvt_pk_bf16_f32 v133, v78, v79
	v_cvt_pk_bf16_f32 v134, v72, v73
	v_cvt_pk_bf16_f32 v135, v74, v75
	v_cvt_pk_bf16_f32 v136, v68, v69
	v_cvt_pk_bf16_f32 v137, v70, v71
	v_cvt_pk_bf16_f32 v138, v64, v65
	v_cvt_pk_bf16_f32 v139, v66, v67
	global_store_dwordx2 v[130:131], v[132:133], off
	global_store_dwordx2 v[130:131], v[134:135], off offset:32
	global_store_dwordx2 v[130:131], v[136:137], off offset:256
	global_store_dwordx2 v[130:131], v[138:139], off offset:288
	v_lshl_add_u64 v[130:131], v[130:131], 0, s[30:31]
	v_cvt_pk_bf16_f32 v132, v60, v61
	v_cvt_pk_bf16_f32 v133, v62, v63
	v_cvt_pk_bf16_f32 v134, v56, v57
	v_cvt_pk_bf16_f32 v135, v58, v59
	v_cvt_pk_bf16_f32 v136, v52, v53
	v_cvt_pk_bf16_f32 v137, v54, v55
	v_cvt_pk_bf16_f32 v138, v48, v49
	v_cvt_pk_bf16_f32 v139, v50, v51
	global_store_dwordx2 v[130:131], v[132:133], off
	global_store_dwordx2 v[130:131], v[134:135], off offset:32
	global_store_dwordx2 v[130:131], v[136:137], off offset:256
	global_store_dwordx2 v[130:131], v[138:139], off offset:288
	v_lshl_add_u64 v[130:131], v[130:131], 0, s[28:29]
	v_cvt_pk_bf16_f32 v132, v44, v45
	v_cvt_pk_bf16_f32 v133, v46, v47
	v_cvt_pk_bf16_f32 v134, v40, v41
	v_cvt_pk_bf16_f32 v135, v42, v43
	v_cvt_pk_bf16_f32 v136, v36, v37
	v_cvt_pk_bf16_f32 v137, v38, v39
	v_cvt_pk_bf16_f32 v138, v32, v33
	v_cvt_pk_bf16_f32 v139, v34, v35
	global_store_dwordx2 v[130:131], v[132:133], off
	global_store_dwordx2 v[130:131], v[134:135], off offset:32
	global_store_dwordx2 v[130:131], v[136:137], off offset:256
	global_store_dwordx2 v[130:131], v[138:139], off offset:288
	v_lshl_add_u64 v[130:131], v[130:131], 0, s[28:29]
	v_cvt_pk_bf16_f32 v132, v28, v29
	v_cvt_pk_bf16_f32 v133, v30, v31
	v_cvt_pk_bf16_f32 v134, v24, v25
	v_cvt_pk_bf16_f32 v135, v26, v27
	v_cvt_pk_bf16_f32 v136, v20, v21
	v_cvt_pk_bf16_f32 v137, v22, v23
	v_cvt_pk_bf16_f32 v138, v16, v17
	v_cvt_pk_bf16_f32 v139, v18, v19
	global_store_dwordx2 v[130:131], v[132:133], off
	global_store_dwordx2 v[130:131], v[134:135], off offset:32
	global_store_dwordx2 v[130:131], v[136:137], off offset:256
	global_store_dwordx2 v[130:131], v[138:139], off offset:288
	v_lshl_add_u64 v[130:131], v[130:131], 0, s[28:29]
	v_cvt_pk_bf16_f32 v132, v12, v13
	v_cvt_pk_bf16_f32 v133, v14, v15
	v_cvt_pk_bf16_f32 v134, v8, v9
	v_cvt_pk_bf16_f32 v135, v10, v11
	v_cvt_pk_bf16_f32 v136, v4, v5
	v_cvt_pk_bf16_f32 v137, v6, v7
	v_cvt_pk_bf16_f32 v138, v0, v1
	v_cvt_pk_bf16_f32 v139, v2, v3
	global_store_dwordx2 v[130:131], v[132:133], off
	global_store_dwordx2 v[130:131], v[134:135], off offset:32
	global_store_dwordx2 v[130:131], v[136:137], off offset:256
	global_store_dwordx2 v[130:131], v[138:139], off offset:288
	s_branch .LBB0_234
; __device__ __forceinline__ float sigmoid_f(float x) { return __builtin_amdgcn_rcpf(1.0f + __expf(-x)); }
; __device__ __forceinline__ float logsigmoid_f(float x) { return fminf(x, 0.f) - __logf(1.0f + __expf(-fabsf(x))); }
;     __device__ __forceinline__ void st4(bf16_t* p, f32x4 v) const { u32x2 w; w.x = cvt_pk_bf16(v[0], v[1]); w.y = cvt_pk_bf16(v[2], v[3]); *(u32x2*)p = w; }
;     __device__ __forceinline__ void operator()(const f32x4 (&acc)[2][2][4][2], const pg8::Unit& u, int wr, int wc, int fr, int fq) const {
;     ...
;                             const int cc = cc0 + bj * 128 + n * 16; const f32x4 v = acc[ai][bj][m][n];
;                             if (pn == 5) st4(V + ((size_t)bidx * SKV + (isctx ? tok : TCX + tok)) * 256 + cc, v);
;                             else if (pn < 14) st4(MQK + (size_t)gr * 2048 + (pn - 6) * 256 + cc, v);
;                             else if (pn < 18) st4(MV + (size_t)gr * 1024 + (pn - 14) * 256 + cc, v);
;                             else if (pn < 22) { if (!isctx) { f32x4 s; s[0] = sigmoid_f(v[0]); s[1] = sigmoid_f(v[1]); s[2] = sigmoid_f(v[2]); s[3] = sigmoid_f(v[3]); st4(MO + (size_t)gr * 1024 + (pn - 18) * 256 + cc, s); } }
;                             else if (cc < 32) {
;                                 f32x4 t = v + *(const f32x4*)(gb + cc);
;                                 if (fq >= 2) { t[0] = logsigmoid_f(t[0]); t[1] = logsigmoid_f(t[1]); t[2] = logsigmoid_f(t[2]); t[3] = logsigmoid_f(t[3]); }
;                                 *(f32x4*)(GT + (size_t)gr * 32 + cc) = t;
;                             }
.Lwin_gen:
	s_mov_b64 s[30:31], -1
	s_and_b64 vcc, exec, s[20:21]
	s_cbranch_vccz .LBB0_267
	s_mov_b64 s[28:29], -1
	s_and_b64 vcc, exec, s[22:23]
	s_cbranch_vccz .LBB0_264
	s_and_b64 vcc, exec, s[70:71]
	s_cbranch_vccz .LBB0_261
	s_and_b64 vcc, exec, s[68:69]
	s_cbranch_vccz .LBB0_257
	v_cmp_gt_i32_e32 vcc, 32, v134
	s_and_saveexec_b64 s[16:17], vcc
	s_cbranch_execz .LBB0_256
	v_readlane_b32 s48, v255, 47
	v_ashrrev_i32_e32 v135, 31, v134
	v_readlane_b32 s49, v255, 48
	v_readlane_b32 s54, v255, 53
	v_readlane_b32 s55, v255, 54
	v_lshl_add_u64 v[130:131], v[134:135], 2, s[48:49]
	global_load_dwordx4 v[130:133], v[130:131], off
	v_readlane_b32 s50, v255, 49
	v_readlane_b32 s51, v255, 50
	v_readlane_b32 s52, v255, 51
	v_readlane_b32 s53, v255, 52
	s_waitcnt vmcnt(0)
	v_pk_add_f32 v[132:133], v[128:129], v[132:133]
	v_pk_add_f32 v[130:131], v[126:127], v[130:131]
	s_and_saveexec_b64 s[54:55], s[36:37]
	s_cbranch_execz .LBB0_255
	s_mov_b32 s19, 0xbfb8aa3b
	v_max_f32_e32 v136, v130, v130
	v_mul_f32_e64 v130, |v130|, s19
	v_exp_f32_e32 v130, v130
	s_mov_b32 s3, 0x800000
	s_mov_b32 s28, 0x3f317217
	s_mov_b32 s29, 0x7f800000
	v_add_f32_e32 v130, 1.0, v130
	v_cmp_gt_f32_e32 vcc, s3, v130
	v_mov_b32_e32 v158, 0x41b17218
	v_min_f32_e32 v136, 0, v136
	v_cndmask_b32_e64 v137, 0, 32, vcc
	v_ldexp_f32 v130, v130, v137
	v_log_f32_e32 v130, v130
	s_mov_b32 s2, 0x800000
	v_mul_f32_e32 v137, 0x3f317217, v130
	v_fma_f32 v137, v130, s28, -v137
	v_fmac_f32_e32 v137, 0x3377d1cf, v130
	v_fmac_f32_e32 v137, 0x3f317217, v130
	v_cmp_lt_f32_e64 s[50:51], |v130|, s29
	s_nop 1
	v_cndmask_b32_e64 v130, v130, v137, s[50:51]
	v_cndmask_b32_e32 v137, 0, v158, vcc
	v_sub_f32_e32 v130, v130, v137
	v_max_f32_e32 v137, v131, v131
	v_mul_f32_e64 v131, |v131|, s19
	v_exp_f32_e32 v131, v131
	v_min_f32_e32 v137, 0, v137
	v_add_f32_e32 v131, 1.0, v131
	v_cmp_gt_f32_e32 vcc, s3, v131
	s_nop 1
	v_cndmask_b32_e64 v140, 0, 32, vcc
	v_ldexp_f32 v131, v131, v140
	v_log_f32_e32 v131, v131
	s_nop 0
	v_mul_f32_e32 v140, 0x3f317217, v131
	v_fma_f32 v140, v131, s28, -v140
	v_fmac_f32_e32 v140, 0x3377d1cf, v131
	v_fmac_f32_e32 v140, 0x3f317217, v131
	v_cmp_lt_f32_e64 s[50:51], |v131|, s29
	s_nop 1
	v_cndmask_b32_e64 v131, v131, v140, s[50:51]
	v_cndmask_b32_e32 v140, 0, v158, vcc
	v_sub_f32_e32 v131, v131, v140
	v_max_f32_e32 v140, v132, v132
	v_mul_f32_e64 v132, |v132|, s19
	v_exp_f32_e32 v132, v132
	v_min_f32_e32 v140, 0, v140
	v_pk_add_f32 v[130:131], v[136:137], v[130:131] neg_lo:[0,1] neg_hi:[0,1]
	v_add_f32_e32 v132, 1.0, v132
	v_cmp_gt_f32_e32 vcc, s3, v132
	s_nop 1
	v_cndmask_b32_e64 v141, 0, 32, vcc
	v_ldexp_f32 v132, v132, v141
	v_log_f32_e32 v132, v132
	s_nop 0
	v_mul_f32_e32 v141, 0x3f317217, v132
	v_fma_f32 v141, v132, s28, -v141
	v_fmac_f32_e32 v141, 0x3377d1cf, v132
	v_fmac_f32_e32 v141, 0x3f317217, v132
	v_cmp_lt_f32_e64 s[50:51], |v132|, s29
	s_nop 1
	v_cndmask_b32_e64 v132, v132, v141, s[50:51]
	v_cndmask_b32_e32 v141, 0, v158, vcc
	v_sub_f32_e32 v132, v132, v141
	v_max_f32_e32 v141, v133, v133
	v_mul_f32_e64 v133, |v133|, s19
	v_exp_f32_e32 v133, v133
	v_min_f32_e32 v141, 0, v141
	v_add_f32_e32 v133, 1.0, v133
	v_cmp_gt_f32_e32 vcc, s3, v133
	s_nop 1
	v_cndmask_b32_e64 v155, 0, 32, vcc
	v_ldexp_f32 v133, v133, v155
	v_log_f32_e32 v133, v133
	s_nop 0
	v_mul_f32_e32 v155, 0x3f317217, v133
	v_fma_f32 v155, v133, s28, -v155
	v_fmac_f32_e32 v155, 0x3377d1cf, v133
	v_fmac_f32_e32 v155, 0x3f317217, v133
	v_cmp_lt_f32_e64 s[50:51], |v133|, s29
	s_nop 1
	v_cndmask_b32_e64 v133, v133, v155, s[50:51]
	v_cndmask_b32_e32 v155, 0, v158, vcc
	v_sub_f32_e32 v133, v133, v155
	v_pk_add_f32 v[132:133], v[140:141], v[132:133] neg_lo:[0,1] neg_hi:[0,1]
